# v83 + 60 bytes of s_nop after the combine phase barrier: later phases (GEMM loops P3..P9) back at the baseline byte offsets modulo 64
# speedup vs baseline: 1.0065x; 1.0065x over previous
.LBB0_765:
	s_or_b64 exec, exec, s[0:1]
	s_add_u32 s24, s86, 0x30800
	s_addc_u32 s25, s87, 0
	s_and_b32 s14, s76, 1
	s_cmpk_lt_i32 s92, 0x100
	s_cselect_b64 s[0:1], -1, 0
	v_writelane_b32 v255, s0, 14
	s_mov_b64 s[54:55], -1
	v_mov_b32_e32 v187, 0
	v_writelane_b32 v255, s1, 15
	s_lshr_b32 s0, s70, 29
	s_add_i32 s0, s92, s0
	s_ashr_i32 s2, s0, 3
	s_and_b32 s0, s0, -8
	s_sub_i32 s93, s92, s0
	s_lshl_b32 s1, s93, 5
	s_add_u32 s28, s86, 0x12000000
	s_addc_u32 s29, s87, 0
	s_add_u32 s18, s86, 0x50800
	s_addc_u32 s19, s87, 0
	s_cmp_lt_i32 s93, 0
	s_cselect_b64 s[4:5], -1, 0
	v_writelane_b32 v254, s4, 45
	s_mul_i32 s6, s93, 33
	v_writelane_b32 v255, s2, 20
	v_writelane_b32 v254, s5, 46
	s_and_b64 s[4:5], s[4:5], exec
	s_cselect_b32 s1, s6, s1
	s_add_i32 s1, s1, s2
	s_ashr_i32 s4, s1, 31
	s_lshr_b32 s4, s4, 27
	s_add_i32 s4, s1, s4
	s_ashr_i32 s5, s4, 5
	s_and_b32 s4, s4, 0xffe0
	s_sub_i32 s1, s1, s4
	s_bfe_i32 s4, s1, 0x80000
	s_bfe_u32 s4, s4, 0x3000c
	s_add_i32 s4, s1, s4
	s_bfe_i32 s6, s4, 0x80000
	s_and_b32 s4, s4, 0xf8
	s_sub_i32 s1, s1, s4
	s_lshl_b32 s5, s5, 3
	s_sext_i32_i16 s6, s6
	s_sext_i32_i8 s1, s1
	s_lshr_b32 s12, s6, 3
	s_add_i32 s10, s5, s1
	s_ashr_i32 s1, s6, 3
	v_writelane_b32 v255, s1, 16
	s_mov_b32 s4, s10
	s_mov_b32 s6, s12
	s_ashr_i32 s11, s10, 31
	v_writelane_b32 v254, s4, 49
	v_writelane_b32 v255, s6, 26
	s_bfe_i64 s[58:59], s[12:13], 0x100000
	v_writelane_b32 v254, s5, 50
	s_lshl_b64 s[4:5], s[10:11], 19
	v_writelane_b32 v255, s7, 27
	s_lshl_b64 s[6:7], s[58:59], 19
	s_add_u32 s30, s38, s6
	s_addc_u32 s31, s39, s7
	s_add_u32 s34, s30, 0x40000
	s_addc_u32 s35, s31, 0
	s_add_u32 s36, s8, s4
	s_addc_u32 s37, s9, s5
	s_add_u32 s48, s36, 0x40000
	s_addc_u32 s49, s37, 0
	s_add_u32 s52, s30, 0x40080
	s_addc_u32 s53, s31, 0
	s_lshl_b32 s1, s76, 5
	s_mov_b32 s0, 0
	v_writelane_b32 v254, s1, 13
	s_movk_i32 s13, 0x7fff
	s_brev_b32 s16, 64
	s_mov_b32 s17, 0x49800000
	s_mov_b32 s51, 0x1fffe0
	s_mov_b64 s[56:57], 0x80
	v_mov_b32_e32 v227, 1
	v_mov_b64_e32 v[188:189], 0x100
	v_mov_b64_e32 v[190:191], 0xff
	s_waitcnt lgkmcnt(0)
	s_barrier
	s_nop 0
	s_nop 0
	s_nop 0
	s_nop 0
	s_nop 0
	s_nop 0
	s_nop 0
	s_nop 0
	s_nop 0
	s_nop 0
	s_nop 0
	s_nop 0
	s_nop 0
	s_nop 0
	s_nop 0
	s_branch .LBB0_768
